# phase 7 (y_a = B*conv3(C*x)) rewritten by hand: conv weights loaded once, scalar row decode, all loads of an item issued together
# speedup vs baseline: 1.0164x; 1.0150x over previous
.LBB0_2765:
	s_cmp_lt_i32 s30, 8
	s_cselect_b64 s[4:5], -1, 0
	s_and_b64 s[0:1], s[4:5], s[0:1]
	s_andn2_b64 vcc, exec, s[0:1]
	s_cbranch_vccnz .LBB0_2798
	v_and_b32_e32 v1, 0x3ff, v0
	v_and_b32_e32 v2, 63, v0
	s_nop 0
	v_readfirstlane_b32 s0, v1
	v_readlane_b32 s8, v238, 29
	v_readlane_b32 s9, v238, 30
	v_readlane_b32 s10, v238, 9
	v_readlane_b32 s11, v238, 10
	s_nop 4
	s_lshr_b32 s0, s0, 6
	s_and_b32 s1, s0, 1
	s_lshl_b32 s1, s1, 6
	v_add_u32_e32 v2, s1, v2
	v_lshlrev_b32_e32 v3, 4, v2
	v_lshlrev_b32_e32 v4, 5, v2
	s_lshr_b32 s3, s0, 1
	s_lshl_b32 s6, s2, 2
	s_add_i32 s6, s6, s3
	s_add_u32 s12, s8, 0x1000
	s_addc_u32 s13, s9, 0
	s_add_u32 s16, s8, 0x2000
	s_addc_u32 s17, s9, 0
	global_load_dwordx4 v[8:11], v4, s[8:9]
	global_load_dwordx4 v[12:15], v4, s[8:9] offset:16
	global_load_dwordx4 v[16:19], v4, s[12:13]
	global_load_dwordx4 v[20:23], v4, s[12:13] offset:16
	global_load_dwordx4 v[24:27], v4, s[16:17]
	global_load_dwordx4 v[28:31], v4, s[16:17] offset:16
.Lya_loop:
	s_lshl_b32 s19, s6, 11
	s_add_u32 s46, s64, s19
	s_addc_u32 s47, s65, 0
	s_add_u32 s48, s20, s19
	s_addc_u32 s49, s21, 0
	s_mov_b32 s40, 0
	s_mov_b32 s41, 0
	s_sub_i32 s7, s6, 1
	s_sub_i32 s18, s6, 2
	s_cmpk_lt_u32 s6, 0x4000
	s_cbranch_scc0 .Lya_notA
	s_and_b32 s22, s6, 0x7ff
	s_lshr_b32 s23, s6, 11
	s_lshl_b32 s23, s23, 4
	s_addk_i32 s23, 0x4400
	s_add_i32 s33, s23, 15
	s_cmp_lg_u32 s22, 0
	s_cselect_b32 s7, s7, s33
	s_add_i32 s33, s23, 14
	s_add_i32 s33, s33, s22
	s_cmp_gt_u32 s22, 1
	s_cselect_b32 s18, s18, s33
	s_branch .Lya_rows
.Lya_notA:
	s_cmpk_lt_u32 s6, 0x4400
	s_cbranch_scc0 .Lya_C
	s_and_b32 s22, s6, 7
	s_sub_i32 s23, s6, 0x4000
	s_lshr_b32 s23, s23, 3
	s_cmp_gt_u32 s22, 0
	s_cbranch_scc1 .Lya_b1
	s_lshl_b32 s33, s23, 1
	s_add_i32 s33, s33, 1
	s_lshl_b32 s33, s33, 12
	s_add_u32 s42, s10, s33
	s_addc_u32 s43, s11, 0
	s_mov_b32 s40, 1
.Lya_b1:
	s_cmp_gt_u32 s22, 1
	s_cbranch_scc1 .Lya_rows
	s_lshl_b32 s33, s23, 1
	s_add_i32 s33, s33, s22
	s_lshl_b32 s33, s33, 12
	s_add_u32 s44, s10, s33
	s_addc_u32 s45, s11, 0
	s_mov_b32 s41, 1
	s_branch .Lya_rows
.Lya_C:
	s_and_b32 s22, s6, 15
	s_cmp_gt_u32 s22, 0
	s_cselect_b32 s40, 0, 2
	s_cmp_gt_u32 s22, 1
	s_cselect_b32 s41, 0, 2
.Lya_rows:
	global_load_dwordx4 v[32:35], v3, s[46:47]
	global_load_dwordx4 v[36:39], v3, s[48:49]
	s_cmp_eq_u32 s40, 0
	s_cbranch_scc0 .Lya_l1n
	s_lshl_b32 s33, s7, 11
	s_add_u32 s42, s64, s33
	s_addc_u32 s43, s65, 0
	global_load_dwordx4 v[40:43], v3, s[42:43]
	s_branch .Lya_l0
.Lya_l1n:
	s_cmp_eq_u32 s40, 1
	s_cbranch_scc0 .Lya_l0
	global_load_dwordx4 v[56:59], v4, s[42:43]
	global_load_dwordx4 v[60:63], v4, s[42:43] offset:16
.Lya_l0:
	s_cmp_eq_u32 s41, 0
	s_cbranch_scc0 .Lya_l0n
	s_lshl_b32 s33, s18, 11
	s_add_u32 s44, s64, s33
	s_addc_u32 s45, s65, 0
	global_load_dwordx4 v[48:51], v3, s[44:45]
	s_branch .Lya_ld
.Lya_l0n:
	s_cmp_eq_u32 s41, 1
	s_cbranch_scc0 .Lya_ld
	global_load_dwordx4 v[64:67], v4, s[44:45]
	global_load_dwordx4 v[68:71], v4, s[44:45] offset:16
.Lya_ld:
	s_waitcnt vmcnt(0)
	s_cmp_eq_u32 s40, 0
	s_cbranch_scc0 .Lya_u1n
	v_lshlrev_b32_e32 v56, 16, v40
	v_and_b32_e32 v57, 0xffff0000, v40
	v_lshlrev_b32_e32 v58, 16, v41
	v_and_b32_e32 v59, 0xffff0000, v41
	v_lshlrev_b32_e32 v60, 16, v42
	v_and_b32_e32 v61, 0xffff0000, v42
	v_lshlrev_b32_e32 v62, 16, v43
	v_and_b32_e32 v63, 0xffff0000, v43
	s_branch .Lya_u0
.Lya_u1n:
	s_cmp_eq_u32 s40, 1
	s_cbranch_scc1 .Lya_u0
	v_mov_b32_e32 v56, 0
	v_mov_b32_e32 v57, 0
	v_mov_b32_e32 v58, 0
	v_mov_b32_e32 v59, 0
	v_mov_b32_e32 v60, 0
	v_mov_b32_e32 v61, 0
	v_mov_b32_e32 v62, 0
	v_mov_b32_e32 v63, 0
.Lya_u0:
	s_cmp_eq_u32 s41, 0
	s_cbranch_scc0 .Lya_u0n
	v_lshlrev_b32_e32 v64, 16, v48
	v_and_b32_e32 v65, 0xffff0000, v48
	v_lshlrev_b32_e32 v66, 16, v49
	v_and_b32_e32 v67, 0xffff0000, v49
	v_lshlrev_b32_e32 v68, 16, v50
	v_and_b32_e32 v69, 0xffff0000, v50
	v_lshlrev_b32_e32 v70, 16, v51
	v_and_b32_e32 v71, 0xffff0000, v51
	s_branch .Lya_cmp
.Lya_u0n:
	s_cmp_eq_u32 s41, 1
	s_cbranch_scc1 .Lya_cmp
	v_mov_b32_e32 v64, 0
	v_mov_b32_e32 v65, 0
	v_mov_b32_e32 v66, 0
	v_mov_b32_e32 v67, 0
	v_mov_b32_e32 v68, 0
	v_mov_b32_e32 v69, 0
	v_mov_b32_e32 v70, 0
	v_mov_b32_e32 v71, 0
.Lya_cmp:
	v_lshlrev_b32_e32 v72, 16, v32
	v_and_b32_e32 v73, 0xffff0000, v32
	v_lshlrev_b32_e32 v74, 16, v33
	v_and_b32_e32 v75, 0xffff0000, v33
	v_lshlrev_b32_e32 v76, 16, v34
	v_and_b32_e32 v77, 0xffff0000, v34
	v_lshlrev_b32_e32 v78, 16, v35
	v_and_b32_e32 v79, 0xffff0000, v35
	v_lshlrev_b32_e32 v80, 16, v36
	v_and_b32_e32 v81, 0xffff0000, v36
	v_lshlrev_b32_e32 v82, 16, v37
	v_and_b32_e32 v83, 0xffff0000, v37
	v_lshlrev_b32_e32 v84, 16, v38
	v_and_b32_e32 v85, 0xffff0000, v38
	v_lshlrev_b32_e32 v86, 16, v39
	v_and_b32_e32 v87, 0xffff0000, v39
	v_pk_mul_f32 v[88:89], v[56:57], v[16:17]
	v_pk_mul_f32 v[90:91], v[58:59], v[18:19]
	v_pk_mul_f32 v[92:93], v[60:61], v[20:21]
	v_pk_mul_f32 v[94:95], v[62:63], v[22:23]
	v_pk_fma_f32 v[88:89], v[64:65], v[8:9], v[88:89]
	v_pk_fma_f32 v[90:91], v[66:67], v[10:11], v[90:91]
	v_pk_fma_f32 v[92:93], v[68:69], v[12:13], v[92:93]
	v_pk_fma_f32 v[94:95], v[70:71], v[14:15], v[94:95]
	v_pk_fma_f32 v[88:89], v[24:25], v[72:73], v[88:89]
	v_pk_fma_f32 v[90:91], v[26:27], v[74:75], v[90:91]
	v_pk_fma_f32 v[92:93], v[28:29], v[76:77], v[92:93]
	v_pk_fma_f32 v[94:95], v[30:31], v[78:79], v[94:95]
	v_pk_mul_f32 v[88:89], v[88:89], v[80:81]
	v_pk_mul_f32 v[90:91], v[90:91], v[82:83]
	v_pk_mul_f32 v[92:93], v[92:93], v[84:85]
	v_pk_mul_f32 v[94:95], v[94:95], v[86:87]
	v_cvt_pk_bf16_f32 v96, v88, v89
	v_cvt_pk_bf16_f32 v97, v90, v91
	v_cvt_pk_bf16_f32 v98, v92, v93
	v_cvt_pk_bf16_f32 v99, v94, v95
	global_store_dwordx4 v3, v[96:99], s[48:49]
	s_addk_i32 s6, 0x400
	s_cmpk_lt_u32 s6, 0x4480
	s_cbranch_scc1 .Lya_loop
